# GLA scan state loop: Q.S and S-update LDS fragment reads hoisted into a ring of quads with counted lgkmcnt waits
# baseline (speedup 1.0000x reference)
; #define LAS __attribute__((address_space(3)))
; #define MFMA32(a, b, c) __builtin_amdgcn_mfma_f32_32x32x16_bf16((a), (b), (c), 0, 0, 0)
; template <int PASS>
; __device__ __forceinline__ void gla_scan3(LAS unsigned char* lds, bf16_t* P  , const bf16_t* QM, const bf16_t* KM, const bf16_t* AQ, const float* EL, bf16_t* OB  , float* SEND, float* DSUM) {
;     ...
; #pragma unroll
;                 for (int kt = 0; kt < 4; ++kt)
; #pragma unroll
;                     for (int g4 = 0; g4 < 4; ++g4) { const f32x4 ev = *(const LAS f32x4*)(el + 32 * kt + 8 * g4 + 4 * h);
; #pragma unroll
;                         for (int e = 0; e < 4; ++e) S[kt][4 * g4 + e] *= ev[e]; }
;                 bf16x8 Vf[4];
; #pragma unroll
;                 for (int ks = 0; ks < 4; ++ks) Vf[ks] = frag_tr(Vb, 136, 32 * w, ks, lane);
;                 if (PASS == 1) {
;                     f32x16 O[2];
; #pragma unroll
;                     for (int mt = 0; mt < 2; ++mt) {
; #pragma unroll
;                         for (int x = 0; x < 16; ++x) O[mt][x] = 0.f;
; #pragma unroll
;                         for (int ks = 0; ks < 4; ++ks) if (ks < 2 * mt + 2) O[mt] = MFMA32(frag_perm(Ab, 72, 32 * mt + r, ks, h), Vf[ks], O[mt]);
;                     }
; #pragma unroll
;                     for (int ks = 0; ks < 8; ++ks) {
;                         const bf16x8 sp = pack_step(S[ks >> 1], ks & 1);
; #pragma unroll
;                         for (int mt = 0; mt < 2; ++mt) O[mt] = MFMA32(frag_perm(Qm, 136, 32 * mt + r, ks, h), sp, O[mt]);
.LBB0_272:
	s_bitcmp1_b32 s63, 0
	s_cselect_b32 s0, 0xf200, 0
	v_bfe_u32 v115, v0, 5, 1
	s_add_i32 s67, s0, 0
	v_lshl_add_u32 v74, v115, 4, s67
	ds_read_b128 v[66:69], v74 offset:61440
	ds_read_b128 v[70:73], v74 offset:61472
	ds_read_b128 v[134:137], v74 offset:61504
	ds_read_b128 v[138:141], v74 offset:61536
	ds_read_b128 v[142:145], v74 offset:61568
	ds_read_b128 v[146:149], v74 offset:61600
	ds_read_b128 v[150:153], v74 offset:61632
	ds_read_b128 v[154:157], v74 offset:61664
	ds_read_b128 v[158:161], v74 offset:61696
	ds_read_b128 v[162:165], v74 offset:61728
	ds_read_b128 v[166:169], v74 offset:61760
	ds_read_b128 v[170:173], v74 offset:61792
	ds_read_b128 v[174:177], v74 offset:61824
	s_add_i32 s0, s67, s19
	v_and_b32_e32 v116, 31, v0
	v_lshlrev_b32_e32 v119, 3, v115
	s_waitcnt lgkmcnt(12)
	v_pk_mul_f32 v[50:51], v[50:51], v[66:67]
	v_pk_mul_f32 v[52:53], v[52:53], v[68:69]
	ds_read_b128 v[66:69], v74 offset:61856
	s_waitcnt lgkmcnt(12)
	v_pk_mul_f32 v[54:55], v[54:55], v[70:71]
	v_pk_mul_f32 v[56:57], v[56:57], v[72:73]
	ds_read_b128 v[70:73], v74 offset:61888
	v_mul_u32_u24_e32 v115, 0x440, v115
	v_cvt_pk_bf16_f32 v125, v56, v57
	s_waitcnt lgkmcnt(12)
	v_pk_mul_f32 v[58:59], v[58:59], v[134:135]
	v_pk_mul_f32 v[60:61], v[60:61], v[136:137]
	ds_read_b128 v[134:137], v74 offset:61920
	s_lshl_b32 s68, s48, 6
	s_mov_b64 s[48:49], -1
	s_andn2_b64 vcc, exec, s[46:47]
	s_waitcnt lgkmcnt(12)
	v_pk_mul_f32 v[62:63], v[62:63], v[138:139]
	v_pk_mul_f32 v[64:65], v[64:65], v[140:141]
	s_waitcnt lgkmcnt(11)
	v_pk_mul_f32 v[34:35], v[34:35], v[142:143]
	v_pk_mul_f32 v[36:37], v[36:37], v[144:145]
	s_waitcnt lgkmcnt(10)
	v_pk_mul_f32 v[38:39], v[38:39], v[146:147]
	v_pk_mul_f32 v[40:41], v[40:41], v[148:149]
	s_waitcnt lgkmcnt(9)
	v_pk_mul_f32 v[42:43], v[42:43], v[150:151]
	v_pk_mul_f32 v[44:45], v[44:45], v[152:153]
	s_waitcnt lgkmcnt(8)
	v_pk_mul_f32 v[46:47], v[46:47], v[154:155]
	v_pk_mul_f32 v[48:49], v[48:49], v[156:157]
	s_waitcnt lgkmcnt(7)
	v_pk_mul_f32 v[18:19], v[18:19], v[158:159]
	v_pk_mul_f32 v[20:21], v[20:21], v[160:161]
	s_waitcnt lgkmcnt(6)
	v_pk_mul_f32 v[22:23], v[22:23], v[162:163]
	v_pk_mul_f32 v[24:25], v[24:25], v[164:165]
	s_waitcnt lgkmcnt(5)
	v_pk_mul_f32 v[26:27], v[26:27], v[166:167]
	v_pk_mul_f32 v[28:29], v[28:29], v[168:169]
	s_waitcnt lgkmcnt(4)
	v_pk_mul_f32 v[30:31], v[30:31], v[170:171]
	v_pk_mul_f32 v[32:33], v[32:33], v[172:173]
	s_waitcnt lgkmcnt(3)
	v_pk_mul_f32 v[2:3], v[2:3], v[174:175]
	v_pk_mul_f32 v[4:5], v[4:5], v[176:177]
	s_waitcnt lgkmcnt(2)
	v_pk_mul_f32 v[6:7], v[6:7], v[66:67]
	v_pk_mul_f32 v[8:9], v[8:9], v[68:69]
	s_waitcnt lgkmcnt(1)
	v_pk_mul_f32 v[10:11], v[10:11], v[70:71]
	v_pk_mul_f32 v[12:13], v[12:13], v[72:73]
	s_waitcnt lgkmcnt(0)
	v_pk_mul_f32 v[14:15], v[14:15], v[134:135]
	v_bfe_u32 v66, v0, 2, 2
	v_lshrrev_b32_e32 v67, 3, v0
	v_and_or_b32 v66, v67, 4, v66
	v_lshlrev_b32_e32 v67, 1, v0
	v_and_b32_e32 v117, 32, v67
	v_mul_u32_u24_e32 v118, 0x110, v66
	v_lshlrev_b32_e32 v66, 3, v0
	v_add_u32_e32 v67, s0, v117
	v_and_b32_e32 v114, 24, v66
	v_add3_u32 v66, v67, v114, v118
	ds_read_b64_tr_b16 v[110:111], v66 offset:34816
	ds_read_b64_tr_b16 v[112:113], v66 offset:36992
	ds_read_b64_tr_b16 v[106:107], v66 offset:39168
	ds_read_b64_tr_b16 v[108:109], v66 offset:41344
	ds_read_b64_tr_b16 v[102:103], v66 offset:43520
	ds_read_b64_tr_b16 v[104:105], v66 offset:45696
	ds_read_b64_tr_b16 v[98:99], v66 offset:47872
	ds_read_b64_tr_b16 v[100:101], v66 offset:50048
	v_mul_u32_u24_e32 v66, 0x90, v116
	v_add3_u32 v74, s67, v66, v119
	v_add_u32_e32 v70, 0xc800, v74
	v_pk_mul_f32 v[16:17], v[16:17], v[136:137]
	ds_read2_b64 v[66:69], v70 offset0:128 offset1:130
	ds_read2_b64 v[70:73], v70 offset0:132 offset1:134
	v_add_u32_e32 v124, 0xd800, v74
	s_waitcnt lgkmcnt(1)
	v_mfma_f32_32x32x16_bf16 v[82:97], v[66:69], v[110:113], 0
	ds_read2_b64 v[66:69], v124 offset0:192 offset1:194
	ds_read2_b64 v[120:123], v124 offset0:196 offset1:198
	s_waitcnt lgkmcnt(2)
	v_mfma_f32_32x32x16_bf16 v[82:97], v[70:73], v[106:109], v[82:97]
	s_waitcnt lgkmcnt(1)
	v_mfma_f32_32x32x16_bf16 v[66:81], v[66:69], v[110:113], 0
	s_waitcnt lgkmcnt(0)
	v_mfma_f32_32x32x16_bf16 v[66:81], v[120:123], v[106:109], v[66:81]
	ds_read2_b64 v[120:123], v124 offset0:200 offset1:202
	s_waitcnt lgkmcnt(0)
	v_mfma_f32_32x32x16_bf16 v[66:81], v[120:123], v[102:105], v[66:81]
	ds_read2_b64 v[120:123], v124 offset0:204 offset1:206
	v_cvt_pk_bf16_f32 v124, v54, v55
	s_waitcnt lgkmcnt(0)
	v_mfma_f32_32x32x16_bf16 v[66:81], v[120:123], v[98:101], v[66:81]
	v_mul_u32_u24_e32 v120, 0x110, v116
	v_add3_u32 v119, s67, v120, v119
	ds_read2_b64 v[134:137], v119 offset1:2
	v_cvt_pk_bf16_f32 v122, v50, v51
	v_cvt_pk_bf16_f32 v123, v52, v53
	v_add_u32_e32 v120, 0x2000, v119
	ds_read2_b64 v[138:141], v120 offset0:64 offset1:66
	ds_read2_b64 v[142:145], v120 offset0:68 offset1:70
	ds_read2_b64 v[146:149], v119 offset0:4 offset1:6
	ds_read2_b64 v[150:153], v119 offset0:8 offset1:10
	ds_read2_b64 v[154:157], v120 offset0:72 offset1:74
	ds_read2_b64 v[158:161], v119 offset0:12 offset1:14
	ds_read2_b64 v[162:165], v120 offset0:76 offset1:78
	v_lshlrev_b32_e32 v116, 1, v116
	s_waitcnt lgkmcnt(7)
	v_mfma_f32_32x32x16_bf16 v[82:97], v[134:137], v[122:125], v[82:97]
	ds_read2_b64 v[166:169], v119 offset0:16 offset1:18
	v_add3_u32 v115, s0, v116, v115
	s_waitcnt lgkmcnt(7)
	v_mfma_f32_32x32x16_bf16 v[66:81], v[138:141], v[122:125], v[66:81]
	ds_read2_b64 v[170:173], v120 offset0:80 offset1:82
	v_cvt_pk_bf16_f32 v122, v58, v59
	v_cvt_pk_bf16_f32 v123, v60, v61
	v_cvt_pk_bf16_f32 v124, v62, v63
	v_cvt_pk_bf16_f32 v125, v64, v65
	s_waitcnt lgkmcnt(7)
; __device__ __forceinline__ int crow(int r, int hi) { return (r & 3) + 8 * (r >> 2) + 4 * hi; }
; __device__ __forceinline__ bf16_t f2bf(float f) { return (bf16_t)(cvtpk_s(f, 0.f) & 0xffffu); }
; __device__ __forceinline__ int crow(int x, int h) { return (x & 3) + 8 * (x >> 2) + 4 * h; }
; #define MFMA32(a, b, c) __builtin_amdgcn_mfma_f32_32x32x16_bf16((a), (b), (c), 0, 0, 0)
; template <int PASS>
; __device__ __forceinline__ void gla_scan3(LAS unsigned char* lds, bf16_t* P  , const bf16_t* QM, const bf16_t* KM, const bf16_t* AQ, const float* EL, bf16_t* OB  , float* SEND, float* DSUM) {
;     ...
;                     for (int ks = 0; ks < 8; ++ks) {
;                         const bf16x8 sp = pack_step(S[ks >> 1], ks & 1);
; #pragma unroll
;                         for (int mt = 0; mt < 2; ++mt) O[mt] = MFMA32(frag_perm(Qm, 136, 32 * mt + r, ks, h), sp, O[mt]);
;                     }
; #pragma unroll
;                     for (int mt = 0; mt < 2; ++mt)
; #pragma unroll
;                         for (int x = 0; x < 16; ++x) Vb[(32 * mt + crow(x, h)) * 136 + 32 * w + r] = f2bf(O[mt][x]);
;                 }
; #pragma unroll
;                 for (int ks = 0; ks < 4; ++ks) {
; #pragma unroll
;                     for (int kt = 0; kt < 4; ++kt) S[kt] = MFMA32(frag_tr(Km, 136, 32 * kt, ks, lane), Vf[ks], S[kt]);
	s_nop 0
	v_mfma_f32_32x32x16_bf16 v[66:81], v[142:145], v[122:125], v[66:81]
	ds_read2_b64 v[134:137], v119 offset0:20 offset1:22
	s_waitcnt lgkmcnt(7)
	v_mfma_f32_32x32x16_bf16 v[82:97], v[146:149], v[122:125], v[82:97]
	ds_read2_b64 v[138:141], v120 offset0:84 offset1:86
	v_cvt_pk_bf16_f32 v122, v34, v35
	v_cvt_pk_bf16_f32 v123, v36, v37
	v_cvt_pk_bf16_f32 v124, v38, v39
	v_cvt_pk_bf16_f32 v125, v40, v41
	s_waitcnt lgkmcnt(7)
	s_nop 0
	v_mfma_f32_32x32x16_bf16 v[82:97], v[150:153], v[122:125], v[82:97]
	ds_read2_b64 v[142:145], v119 offset0:24 offset1:26
	s_waitcnt lgkmcnt(7)
	v_mfma_f32_32x32x16_bf16 v[66:81], v[154:157], v[122:125], v[66:81]
	ds_read2_b64 v[146:149], v120 offset0:88 offset1:90
	v_cvt_pk_bf16_f32 v122, v42, v43
	v_cvt_pk_bf16_f32 v123, v44, v45
	v_cvt_pk_bf16_f32 v124, v46, v47
	v_cvt_pk_bf16_f32 v125, v48, v49
	s_waitcnt lgkmcnt(7)
	s_nop 0
	v_mfma_f32_32x32x16_bf16 v[82:97], v[158:161], v[122:125], v[82:97]
	ds_read2_b64 v[150:153], v119 offset0:28 offset1:30
	s_waitcnt lgkmcnt(7)
	v_mfma_f32_32x32x16_bf16 v[66:81], v[162:165], v[122:125], v[66:81]
	ds_read2_b64 v[154:157], v120 offset0:92 offset1:94
	v_cvt_pk_bf16_f32 v122, v18, v19
	v_cvt_pk_bf16_f32 v123, v20, v21
	v_cvt_pk_bf16_f32 v124, v22, v23
	v_cvt_pk_bf16_f32 v125, v24, v25
	s_waitcnt lgkmcnt(7)
	s_nop 0
	v_mfma_f32_32x32x16_bf16 v[82:97], v[166:169], v[122:125], v[82:97]
	s_waitcnt lgkmcnt(6)
	v_mfma_f32_32x32x16_bf16 v[66:81], v[170:173], v[122:125], v[66:81]
	v_cvt_pk_bf16_f32 v122, v26, v27
	v_cvt_pk_bf16_f32 v123, v28, v29
	v_cvt_pk_bf16_f32 v124, v30, v31
	v_cvt_pk_bf16_f32 v125, v32, v33
	s_waitcnt lgkmcnt(5)
	s_nop 0
	v_mfma_f32_32x32x16_bf16 v[82:97], v[134:137], v[122:125], v[82:97]
	s_waitcnt lgkmcnt(4)
	v_mfma_f32_32x32x16_bf16 v[66:81], v[138:141], v[122:125], v[66:81]
	v_cvt_pk_bf16_f32 v122, v2, v3
	v_cvt_pk_bf16_f32 v123, v4, v5
	v_cvt_pk_bf16_f32 v124, v6, v7
	v_cvt_pk_bf16_f32 v125, v8, v9
	s_waitcnt lgkmcnt(3)
	s_nop 0
	v_mfma_f32_32x32x16_bf16 v[82:97], v[142:145], v[122:125], v[82:97]
	s_waitcnt lgkmcnt(2)
	v_mfma_f32_32x32x16_bf16 v[66:81], v[146:149], v[122:125], v[66:81]
	v_cvt_pk_bf16_f32 v122, v10, v11
	v_cvt_pk_bf16_f32 v123, v12, v13
	v_cvt_pk_bf16_f32 v124, v14, v15
	v_cvt_pk_bf16_f32 v125, v16, v17
	s_waitcnt lgkmcnt(1)
	s_nop 0
	v_mfma_f32_32x32x16_bf16 v[82:97], v[150:153], v[122:125], v[82:97]
	s_waitcnt lgkmcnt(0)
	v_mfma_f32_32x32x16_bf16 v[66:81], v[154:157], v[122:125], v[66:81]
	s_nop 8
	v_cvt_pk_bf16_f32 v82, v82, s0
	ds_write_b16 v115, v82 offset:34816
	v_cvt_pk_bf16_f32 v82, v83, s0
	ds_write_b16 v115, v82 offset:35088
	v_cvt_pk_bf16_f32 v82, v84, s0
	ds_write_b16 v115, v82 offset:35360
	v_cvt_pk_bf16_f32 v82, v85, s0
	v_cvt_pk_bf16_f32 v66, v66, s0
	ds_write_b16 v115, v66 offset:43520
	v_cvt_pk_bf16_f32 v66, v67, s0
	ds_write_b16 v115, v66 offset:43792
	v_cvt_pk_bf16_f32 v66, v68, s0
	ds_write_b16 v115, v66 offset:44064
	v_cvt_pk_bf16_f32 v66, v69, s0
	ds_write_b16 v115, v66 offset:44336
	v_cvt_pk_bf16_f32 v66, v70, s0
	ds_write_b16 v115, v82 offset:35632
	v_cvt_pk_bf16_f32 v82, v86, s0
	ds_write_b16 v115, v66 offset:45696
	v_cvt_pk_bf16_f32 v66, v71, s0
	ds_write_b16 v115, v82 offset:36992
	v_cvt_pk_bf16_f32 v82, v87, s0
	ds_write_b16 v115, v66 offset:45968
	v_cvt_pk_bf16_f32 v66, v72, s0
	ds_write_b16 v115, v82 offset:37264
	v_cvt_pk_bf16_f32 v82, v88, s0
	ds_write_b16 v115, v66 offset:46240
	v_cvt_pk_bf16_f32 v66, v73, s0
	ds_write_b16 v115, v82 offset:37536
	v_cvt_pk_bf16_f32 v82, v89, s0
	ds_write_b16 v115, v66 offset:46512
	v_cvt_pk_bf16_f32 v66, v74, s0
	ds_write_b16 v115, v82 offset:37808
	v_cvt_pk_bf16_f32 v82, v90, s0
	ds_write_b16 v115, v66 offset:47872
	v_cvt_pk_bf16_f32 v66, v75, s0
	ds_write_b16 v115, v82 offset:39168
	v_cvt_pk_bf16_f32 v82, v91, s0
	ds_write_b16 v115, v66 offset:48144
	v_cvt_pk_bf16_f32 v66, v76, s0
	ds_write_b16 v115, v82 offset:39440
	v_cvt_pk_bf16_f32 v82, v92, s0
	ds_write_b16 v115, v66 offset:48416
	v_cvt_pk_bf16_f32 v66, v77, s0
	ds_write_b16 v115, v82 offset:39712
	v_cvt_pk_bf16_f32 v82, v93, s0
	ds_write_b16 v115, v66 offset:48688
	v_cvt_pk_bf16_f32 v66, v78, s0
	ds_write_b16 v115, v82 offset:39984
	v_cvt_pk_bf16_f32 v82, v94, s0
	ds_write_b16 v115, v66 offset:50048
	v_cvt_pk_bf16_f32 v66, v79, s0
	ds_write_b16 v115, v82 offset:41344
	v_cvt_pk_bf16_f32 v82, v95, s0
	ds_write_b16 v115, v66 offset:50320
	v_cvt_pk_bf16_f32 v66, v80, s0
	ds_write_b16 v115, v82 offset:41616
	v_cvt_pk_bf16_f32 v82, v96, s0
	ds_write_b16 v115, v66 offset:50592
	v_cvt_pk_bf16_f32 v66, v81, s0
	ds_write_b16 v115, v82 offset:41888
	v_cvt_pk_bf16_f32 v82, v97, s0
	ds_write_b16 v115, v66 offset:50864
	v_add_u32_e32 v66, s67, v117
	ds_write_b16 v115, v82 offset:42160
	v_add3_u32 v70, v66, v114, v118
	ds_read_b64_tr_b16 v[134:135], v70 offset:17408
	ds_read_b64_tr_b16 v[136:137], v70 offset:19584
	ds_read_b64_tr_b16 v[138:139], v70 offset:17472
	ds_read_b64_tr_b16 v[140:141], v70 offset:19648
	ds_read_b64_tr_b16 v[142:143], v70 offset:17536
	ds_read_b64_tr_b16 v[144:145], v70 offset:19712
	ds_read_b64_tr_b16 v[146:147], v70 offset:17600
	ds_read_b64_tr_b16 v[148:149], v70 offset:19776
	ds_read_b64_tr_b16 v[150:151], v70 offset:21760
	ds_read_b64_tr_b16 v[152:153], v70 offset:23936
	ds_read_b64_tr_b16 v[154:155], v70 offset:21824
	ds_read_b64_tr_b16 v[156:157], v70 offset:24000
	s_waitcnt lgkmcnt(10)
; #define MFMA32(a, b, c) __builtin_amdgcn_mfma_f32_32x32x16_bf16((a), (b), (c), 0, 0, 0)
; template <int PASS>
; __device__ __forceinline__ void gla_scan3(LAS unsigned char* lds, bf16_t* P  , const bf16_t* QM, const bf16_t* KM, const bf16_t* AQ, const float* EL, bf16_t* OB  , float* SEND, float* DSUM) {
;     ...
; #pragma unroll
;                 for (int ks = 0; ks < 4; ++ks) {
; #pragma unroll
;                     for (int kt = 0; kt < 4; ++kt) S[kt] = MFMA32(frag_tr(Km, 136, 32 * kt, ks, lane), Vf[ks], S[kt]);
;                 }
;                 if (PASS == 1) {
;                     asm volatile("s_waitcnt lgkmcnt(0)" ::: "memory");
;                     const int rr_ = lane >> 2, c8_ = 8 * (lane & 3);
; #pragma unroll
;                     for (int v = 0; v < 4; ++v) { const int ip_ = rr_ + 16 * v, i_ = dir ? 63 - ip_ : ip_; const int oc_ = head * 256 + hf * 128 + 32 * w + c8_;
;                         bf16_t* dst_ = dir ? P + (size_t)(rb * 64 + i_) * 3072 + oc_ : OB + (size_t)(rb * 64 + i_) * 1024 + oc_;
	v_mfma_f32_32x32x16_bf16 v[50:65], v[134:137], v[110:113], v[50:65]
	ds_read_b64_tr_b16 v[158:159], v70 offset:21888
	ds_read_b64_tr_b16 v[160:161], v70 offset:24064
	v_bfe_u32 v74, v0, 2, 4
	v_or_b32_e32 v0, s66, v114
	v_lshlrev_b32_e32 v0, 1, v0
	s_waitcnt lgkmcnt(10)
	v_mfma_f32_32x32x16_bf16 v[34:49], v[138:141], v[110:113], v[34:49]
	ds_read_b64_tr_b16 v[162:163], v70 offset:21952
	ds_read_b64_tr_b16 v[164:165], v70 offset:24128
	s_waitcnt lgkmcnt(10)
	v_mfma_f32_32x32x16_bf16 v[18:33], v[142:145], v[110:113], v[18:33]
	ds_read_b64_tr_b16 v[134:135], v70 offset:26112
	ds_read_b64_tr_b16 v[136:137], v70 offset:28288
	s_waitcnt lgkmcnt(10)
	v_mfma_f32_32x32x16_bf16 v[2:17], v[146:149], v[110:113], v[2:17]
	ds_read_b64_tr_b16 v[138:139], v70 offset:26176
	ds_read_b64_tr_b16 v[140:141], v70 offset:28352
	s_waitcnt lgkmcnt(10)
	v_mfma_f32_32x32x16_bf16 v[50:65], v[150:153], v[106:109], v[50:65]
	ds_read_b64_tr_b16 v[142:143], v70 offset:26240
	ds_read_b64_tr_b16 v[144:145], v70 offset:28416
	s_waitcnt lgkmcnt(10)
	v_mfma_f32_32x32x16_bf16 v[34:49], v[154:157], v[106:109], v[34:49]
	ds_read_b64_tr_b16 v[146:147], v70 offset:26304
	ds_read_b64_tr_b16 v[148:149], v70 offset:28480
	s_waitcnt lgkmcnt(10)
	v_mfma_f32_32x32x16_bf16 v[18:33], v[158:161], v[106:109], v[18:33]
	ds_read_b64_tr_b16 v[150:151], v70 offset:30464
	ds_read_b64_tr_b16 v[152:153], v70 offset:32640
	s_waitcnt lgkmcnt(10)
	v_mfma_f32_32x32x16_bf16 v[2:17], v[162:165], v[106:109], v[2:17]
	ds_read_b64_tr_b16 v[154:155], v70 offset:30528
	ds_read_b64_tr_b16 v[156:157], v70 offset:32704
	s_waitcnt lgkmcnt(10)
	v_mfma_f32_32x32x16_bf16 v[50:65], v[134:137], v[102:105], v[50:65]
	ds_read_b64_tr_b16 v[158:159], v70 offset:30592
	ds_read_b64_tr_b16 v[160:161], v70 offset:32768
	s_waitcnt lgkmcnt(10)
	v_mfma_f32_32x32x16_bf16 v[34:49], v[138:141], v[102:105], v[34:49]
	ds_read_b64_tr_b16 v[162:163], v70 offset:30656
	ds_read_b64_tr_b16 v[164:165], v70 offset:32832
	s_waitcnt lgkmcnt(10)
	v_mfma_f32_32x32x16_bf16 v[18:33], v[142:145], v[102:105], v[18:33]
	s_waitcnt lgkmcnt(8)
	v_mfma_f32_32x32x16_bf16 v[2:17], v[146:149], v[102:105], v[2:17]
	s_waitcnt lgkmcnt(6)
	v_mfma_f32_32x32x16_bf16 v[50:65], v[150:153], v[98:101], v[50:65]
	s_waitcnt lgkmcnt(4)
	v_mfma_f32_32x32x16_bf16 v[34:49], v[154:157], v[98:101], v[34:49]
	s_waitcnt lgkmcnt(2)
	v_mfma_f32_32x32x16_bf16 v[18:33], v[158:161], v[98:101], v[18:33]
	s_waitcnt lgkmcnt(0)
	v_mfma_f32_32x32x16_bf16 v[2:17], v[162:165], v[98:101], v[2:17]
	v_cndmask_b32_e64 v69, 0, 1, s[46:47]
	v_lshl_add_u64 v[66:67], s[96:97], 0, v[0:1]
	v_or_b32_e32 v68, s68, v74
	v_cmp_ne_u32_e64 s[0:1], 1, v69
	s_cbranch_vccnz .LBB0_274
	v_xor_b32_e32 v69, 63, v68
	v_mad_i64_i32 v[72:73], s[48:49], v69, s79, v[66:67]
	s_mov_b64 s[48:49], 0
